# speedup vs baseline: 1.0153x; 1.0059x over previous
; __device__ __forceinline__ void phase0(const Params& p, int wid_s, char* shm) {
;     ...
;       for (int kk = 0; kk < 32; ++kk) {
;         int k = kg * 32 + kk;
;         float4 w = *(const float4*)(p.w_ada + (size_t)k * 12288 + col);
; #pragma unroll
;         for (int b = 0; b < 12; ++b) {
;           float s = sc[b * 2048 + k];
;           acc[b][0] += s * w.x; acc[b][1] += s * w.y; acc[b][2] += s * w.z; acc[b][3] += s * w.w;
;         }
;       }
.LBB0_123:
	s_mov_b32 s7, 0xfffdc000
	v_add_co_u32_e32 v8, vcc, s7, v66
	v_add_u32_e32 v48, s6, v133
	s_nop 0
	v_addc_co_u32_e32 v9, vcc, -1, v67, vcc
	global_load_dwordx4 v[94:97], v[8:9], off offset:-8
	s_mov_b32 s7, 0xfffe8000
	v_add_co_u32_e32 v200, vcc, s7, v66
	s_nop 0
	v_addc_co_u32_e32 v201, vcc, -1, v67, vcc
	global_load_dwordx4 v[204:207], v[200:201], off offset:-8
	s_mov_b32 s7, 0xffff4000
	v_add_co_u32_e32 v200, vcc, s7, v66
	s_nop 0
	v_addc_co_u32_e32 v201, vcc, -1, v67, vcc
	global_load_dwordx4 v[208:211], v[200:201], off offset:-8
	global_load_dwordx4 v[212:215], v[66:67], off offset:-8
	ds_read_b128 v[2:5], v48 offset:128
	s_mov_b32 s7, 0xfffe8000
	s_add_i32 s6, s6, 16
	s_mov_b64 s[8:9], 0x30000
	s_cmp_eq_u32 s6, 0
	s_waitcnt vmcnt(3) lgkmcnt(0)
	v_pk_fma_f32 v[98:99], v[96:97], v[2:3], v[6:7] op_sel_hi:[1,0,1]
	ds_read_b128 v[6:9], v48 offset:8320
	v_pk_fma_f32 v[92:93], v[94:95], v[2:3], v[92:93] op_sel_hi:[1,0,1]
	s_waitcnt lgkmcnt(0)
	v_pk_fma_f32 v[100:101], v[96:97], v[6:7], v[10:11] op_sel_hi:[1,0,1]
	ds_read_b128 v[10:13], v48 offset:16512
	v_pk_fma_f32 v[90:91], v[94:95], v[6:7], v[90:91] op_sel_hi:[1,0,1]
	s_waitcnt lgkmcnt(0)
	v_pk_fma_f32 v[102:103], v[96:97], v[10:11], v[14:15] op_sel_hi:[1,0,1]
	ds_read_b128 v[14:17], v48 offset:24704
	v_pk_fma_f32 v[88:89], v[94:95], v[10:11], v[88:89] op_sel_hi:[1,0,1]
	s_waitcnt lgkmcnt(0)
	v_pk_fma_f32 v[104:105], v[96:97], v[14:15], v[18:19] op_sel_hi:[1,0,1]
	ds_read_b128 v[18:21], v48 offset:32896
	v_pk_fma_f32 v[86:87], v[94:95], v[14:15], v[86:87] op_sel_hi:[1,0,1]
	s_waitcnt lgkmcnt(0)
	v_pk_fma_f32 v[106:107], v[96:97], v[18:19], v[22:23] op_sel_hi:[1,0,1]
	ds_read_b128 v[22:25], v48 offset:41088
	v_pk_fma_f32 v[84:85], v[94:95], v[18:19], v[84:85] op_sel_hi:[1,0,1]
	s_waitcnt lgkmcnt(0)
	v_pk_fma_f32 v[108:109], v[96:97], v[22:23], v[26:27] op_sel_hi:[1,0,1]
	ds_read_b128 v[26:29], v48 offset:49280
	v_pk_fma_f32 v[82:83], v[94:95], v[22:23], v[82:83] op_sel_hi:[1,0,1]
	s_waitcnt lgkmcnt(0)
	v_pk_fma_f32 v[110:111], v[96:97], v[26:27], v[30:31] op_sel_hi:[1,0,1]
	ds_read_b128 v[30:33], v48 offset:57472
	v_pk_fma_f32 v[80:81], v[94:95], v[26:27], v[80:81] op_sel_hi:[1,0,1]
	s_waitcnt lgkmcnt(0)
	v_pk_fma_f32 v[112:113], v[96:97], v[30:31], v[34:35] op_sel_hi:[1,0,1]
	v_add_u32_e32 v34, 0x10080, v48
	ds_read_b128 v[34:37], v34
	v_pk_fma_f32 v[78:79], v[94:95], v[30:31], v[78:79] op_sel_hi:[1,0,1]
	s_waitcnt lgkmcnt(0)
	v_pk_fma_f32 v[138:139], v[96:97], v[34:35], v[38:39] op_sel_hi:[1,0,1]
	v_add_u32_e32 v38, 0x12080, v48
	ds_read_b128 v[38:41], v38
	v_pk_fma_f32 v[76:77], v[94:95], v[34:35], v[76:77] op_sel_hi:[1,0,1]
	s_waitcnt lgkmcnt(0)
	v_pk_fma_f32 v[140:141], v[96:97], v[38:39], v[42:43] op_sel_hi:[1,0,1]
	v_add_u32_e32 v42, 0x14080, v48
	ds_read_b128 v[42:45], v42
	v_pk_fma_f32 v[74:75], v[94:95], v[38:39], v[74:75] op_sel_hi:[1,0,1]
	s_waitcnt lgkmcnt(0)
	v_pk_fma_f32 v[142:143], v[96:97], v[42:43], v[46:47] op_sel_hi:[1,0,1]
	v_add_u32_e32 v46, 0x16080, v48
	ds_read_b128 v[46:49], v46
	v_pk_fma_f32 v[72:73], v[94:95], v[42:43], v[72:73] op_sel_hi:[1,0,1]
	s_waitcnt lgkmcnt(0)
	v_pk_fma_f32 v[96:97], v[96:97], v[46:47], v[68:69] op_sel_hi:[1,0,1]
	v_pk_fma_f32 v[94:95], v[94:95], v[46:47], v[70:71] op_sel_hi:[1,0,1]
	s_nop 0
	s_mov_b32 s7, 0xffff4000
	s_waitcnt vmcnt(2)
	v_pk_fma_f32 v[92:93], v[204:205], v[2:3], v[92:93] op_sel:[0,1,0]
	v_pk_fma_f32 v[90:91], v[204:205], v[6:7], v[90:91] op_sel:[0,1,0]
	v_pk_fma_f32 v[88:89], v[204:205], v[10:11], v[88:89] op_sel:[0,1,0]
	v_pk_fma_f32 v[86:87], v[204:205], v[14:15], v[86:87] op_sel:[0,1,0]
	v_pk_fma_f32 v[84:85], v[204:205], v[18:19], v[84:85] op_sel:[0,1,0]
	v_pk_fma_f32 v[82:83], v[204:205], v[22:23], v[82:83] op_sel:[0,1,0]
	v_pk_fma_f32 v[80:81], v[204:205], v[26:27], v[80:81] op_sel:[0,1,0]
	v_pk_fma_f32 v[78:79], v[204:205], v[30:31], v[78:79] op_sel:[0,1,0]
	v_pk_fma_f32 v[76:77], v[204:205], v[34:35], v[76:77] op_sel:[0,1,0]
	v_pk_fma_f32 v[74:75], v[204:205], v[38:39], v[74:75] op_sel:[0,1,0]
	v_pk_fma_f32 v[72:73], v[204:205], v[42:43], v[72:73] op_sel:[0,1,0]
	v_pk_fma_f32 v[94:95], v[204:205], v[46:47], v[94:95] op_sel:[0,1,0]
	v_pk_fma_f32 v[2:3], v[206:207], v[2:3], v[98:99] op_sel:[0,1,0]
	s_nop 0
	v_pk_fma_f32 v[6:7], v[206:207], v[6:7], v[100:101] op_sel:[0,1,0]
	v_pk_fma_f32 v[10:11], v[206:207], v[10:11], v[102:103] op_sel:[0,1,0]
	v_pk_fma_f32 v[14:15], v[206:207], v[14:15], v[104:105] op_sel:[0,1,0]
	v_pk_fma_f32 v[18:19], v[206:207], v[18:19], v[106:107] op_sel:[0,1,0]
	v_pk_fma_f32 v[22:23], v[206:207], v[22:23], v[108:109] op_sel:[0,1,0]
	v_pk_fma_f32 v[26:27], v[206:207], v[26:27], v[110:111] op_sel:[0,1,0]
	v_pk_fma_f32 v[30:31], v[206:207], v[30:31], v[112:113] op_sel:[0,1,0]
	v_pk_fma_f32 v[34:35], v[206:207], v[34:35], v[138:139] op_sel:[0,1,0]
	v_pk_fma_f32 v[38:39], v[206:207], v[38:39], v[140:141] op_sel:[0,1,0]
	v_pk_fma_f32 v[42:43], v[206:207], v[42:43], v[142:143] op_sel:[0,1,0]
	v_pk_fma_f32 v[46:47], v[206:207], v[46:47], v[96:97] op_sel:[0,1,0]
	s_waitcnt vmcnt(1)
; __device__ __forceinline__ void phase0(const Params& p, int wid_s, char* shm) {
;     ...
;       for (int kk = 0; kk < 32; ++kk) {
;         int k = kg * 32 + kk;
;         float4 w = *(const float4*)(p.w_ada + (size_t)k * 12288 + col);
; #pragma unroll
;         for (int b = 0; b < 12; ++b) {
;           float s = sc[b * 2048 + k];
;           acc[b][0] += s * w.x; acc[b][1] += s * w.y; acc[b][2] += s * w.z; acc[b][3] += s * w.w;
;         }
;       }
; #pragma unroll
;       for (int b = 0; b < 12; ++b)
; #pragma unroll
;         for (int c = 0; c < 4; ++c) {
;           float v = acc[b][c];
;           v += __shfl_xor(v, 8); v += __shfl_xor(v, 16); v += __shfl_xor(v, 32);
;           acc[b][c] = v;
;         }
	v_pk_fma_f32 v[92:93], v[208:209], v[4:5], v[92:93] op_sel_hi:[1,0,1]
	v_pk_fma_f32 v[90:91], v[208:209], v[8:9], v[90:91] op_sel_hi:[1,0,1]
	v_pk_fma_f32 v[88:89], v[208:209], v[12:13], v[88:89] op_sel_hi:[1,0,1]
	v_pk_fma_f32 v[86:87], v[208:209], v[16:17], v[86:87] op_sel_hi:[1,0,1]
	v_pk_fma_f32 v[84:85], v[208:209], v[20:21], v[84:85] op_sel_hi:[1,0,1]
	v_pk_fma_f32 v[82:83], v[208:209], v[24:25], v[82:83] op_sel_hi:[1,0,1]
	v_pk_fma_f32 v[80:81], v[208:209], v[28:29], v[80:81] op_sel_hi:[1,0,1]
	v_pk_fma_f32 v[78:79], v[208:209], v[32:33], v[78:79] op_sel_hi:[1,0,1]
	v_pk_fma_f32 v[76:77], v[208:209], v[36:37], v[76:77] op_sel_hi:[1,0,1]
	v_pk_fma_f32 v[74:75], v[208:209], v[40:41], v[74:75] op_sel_hi:[1,0,1]
	v_pk_fma_f32 v[72:73], v[208:209], v[44:45], v[72:73] op_sel_hi:[1,0,1]
	v_pk_fma_f32 v[68:69], v[208:209], v[48:49], v[94:95] op_sel_hi:[1,0,1]
	v_pk_fma_f32 v[2:3], v[210:211], v[4:5], v[2:3] op_sel_hi:[1,0,1]
	v_mov_b32_e32 v4, v5
	v_pk_fma_f32 v[98:99], v[210:211], v[8:9], v[6:7] op_sel_hi:[1,0,1]
	v_pk_fma_f32 v[100:101], v[210:211], v[12:13], v[10:11] op_sel_hi:[1,0,1]
	v_pk_fma_f32 v[102:103], v[210:211], v[16:17], v[14:15] op_sel_hi:[1,0,1]
	v_pk_fma_f32 v[104:105], v[210:211], v[20:21], v[18:19] op_sel_hi:[1,0,1]
	v_pk_fma_f32 v[106:107], v[210:211], v[24:25], v[22:23] op_sel_hi:[1,0,1]
	v_pk_fma_f32 v[108:109], v[210:211], v[28:29], v[26:27] op_sel_hi:[1,0,1]
	v_pk_fma_f32 v[110:111], v[210:211], v[32:33], v[30:31] op_sel_hi:[1,0,1]
	v_pk_fma_f32 v[112:113], v[210:211], v[36:37], v[34:35] op_sel_hi:[1,0,1]
	v_pk_fma_f32 v[138:139], v[210:211], v[40:41], v[38:39] op_sel_hi:[1,0,1]
	v_pk_fma_f32 v[140:141], v[210:211], v[44:45], v[42:43] op_sel_hi:[1,0,1]
	v_pk_fma_f32 v[142:143], v[210:211], v[48:49], v[46:47] op_sel_hi:[1,0,1]
	v_lshl_add_u64 v[66:67], v[66:67], 0, s[8:9]
	s_waitcnt vmcnt(0)
	v_pk_fma_f32 v[6:7], v[214:215], v[4:5], v[2:3] op_sel_hi:[1,0,1]
	v_mov_b32_e32 v2, v9
	v_pk_fma_f32 v[90:91], v[212:213], v[2:3], v[90:91] op_sel_hi:[1,0,1]
	v_pk_fma_f32 v[10:11], v[214:215], v[2:3], v[98:99] op_sel_hi:[1,0,1]
	v_mov_b32_e32 v2, v13
	v_pk_fma_f32 v[88:89], v[212:213], v[2:3], v[88:89] op_sel_hi:[1,0,1]
	v_pk_fma_f32 v[14:15], v[214:215], v[2:3], v[100:101] op_sel_hi:[1,0,1]
	v_mov_b32_e32 v2, v17
	v_pk_fma_f32 v[86:87], v[212:213], v[2:3], v[86:87] op_sel_hi:[1,0,1]
	v_pk_fma_f32 v[18:19], v[214:215], v[2:3], v[102:103] op_sel_hi:[1,0,1]
	v_mov_b32_e32 v2, v21
	v_pk_fma_f32 v[84:85], v[212:213], v[2:3], v[84:85] op_sel_hi:[1,0,1]
	v_pk_fma_f32 v[22:23], v[214:215], v[2:3], v[104:105] op_sel_hi:[1,0,1]
	v_mov_b32_e32 v2, v25
	v_pk_fma_f32 v[82:83], v[212:213], v[2:3], v[82:83] op_sel_hi:[1,0,1]
	v_pk_fma_f32 v[26:27], v[214:215], v[2:3], v[106:107] op_sel_hi:[1,0,1]
	v_mov_b32_e32 v2, v29
	v_pk_fma_f32 v[80:81], v[212:213], v[2:3], v[80:81] op_sel_hi:[1,0,1]
	v_pk_fma_f32 v[30:31], v[214:215], v[2:3], v[108:109] op_sel_hi:[1,0,1]
	v_mov_b32_e32 v2, v33
	v_pk_fma_f32 v[78:79], v[212:213], v[2:3], v[78:79] op_sel_hi:[1,0,1]
	v_pk_fma_f32 v[34:35], v[214:215], v[2:3], v[110:111] op_sel_hi:[1,0,1]
	v_mov_b32_e32 v2, v37
	v_pk_fma_f32 v[76:77], v[212:213], v[2:3], v[76:77] op_sel_hi:[1,0,1]
	v_pk_fma_f32 v[38:39], v[214:215], v[2:3], v[112:113] op_sel_hi:[1,0,1]
	v_mov_b32_e32 v2, v41
	v_pk_fma_f32 v[74:75], v[212:213], v[2:3], v[74:75] op_sel_hi:[1,0,1]
	v_pk_fma_f32 v[42:43], v[214:215], v[2:3], v[138:139] op_sel_hi:[1,0,1]
	v_mov_b32_e32 v2, v45
	v_pk_fma_f32 v[72:73], v[212:213], v[2:3], v[72:73] op_sel_hi:[1,0,1]
	v_pk_fma_f32 v[46:47], v[214:215], v[2:3], v[140:141] op_sel_hi:[1,0,1]
	v_mov_b32_e32 v2, v49
	v_pk_fma_f32 v[92:93], v[212:213], v[4:5], v[92:93] op_sel_hi:[1,0,1]
	v_pk_fma_f32 v[70:71], v[212:213], v[2:3], v[68:69] op_sel_hi:[1,0,1]
	v_pk_fma_f32 v[68:69], v[214:215], v[2:3], v[142:143] op_sel_hi:[1,0,1]
	s_cbranch_scc0 .LBB0_123
	v_and_b32_e32 v3, 64, v136
	v_xor_b32_e32 v2, 8, v136
	v_add_u32_e32 v12, 64, v3
	v_cmp_lt_i32_e32 vcc, v2, v12
	v_xor_b32_e32 v4, 16, v136
	v_xor_b32_e32 v13, 32, v136
	v_cndmask_b32_e32 v2, v136, v2, vcc
	v_lshlrev_b32_e32 v54, 2, v2
	ds_bpermute_b32 v28, v54, v14
	ds_bpermute_b32 v29, v54, v15
	ds_bpermute_b32 v44, v54, v18
	ds_bpermute_b32 v45, v54, v19
	ds_bpermute_b32 v48, v54, v84
	ds_bpermute_b32 v49, v54, v85
	ds_bpermute_b32 v16, v54, v10
	ds_bpermute_b32 v17, v54, v11
	v_cmp_lt_i32_e32 vcc, v4, v12
	s_waitcnt lgkmcnt(6)
	v_pk_add_f32 v[28:29], v[14:15], v[28:29]
	s_waitcnt lgkmcnt(4)
	v_pk_add_f32 v[18:19], v[18:19], v[44:45]
	v_cndmask_b32_e32 v4, v136, v4, vcc
	v_lshlrev_b32_e32 v61, 2, v4
	s_waitcnt lgkmcnt(2)
	v_pk_add_f32 v[66:67], v[84:85], v[48:49]
	s_waitcnt lgkmcnt(0)
	v_pk_add_f32 v[16:17], v[10:11], v[16:17]
	ds_bpermute_b32 v36, v61, v28
	ds_bpermute_b32 v37, v61, v29
	ds_bpermute_b32 v40, v54, v86
	ds_bpermute_b32 v41, v54, v87
	ds_bpermute_b32 v44, v61, v18
	ds_bpermute_b32 v45, v61, v19
	ds_bpermute_b32 v84, v61, v66
	ds_bpermute_b32 v85, v61, v67
	ds_bpermute_b32 v24, v61, v16
	ds_bpermute_b32 v25, v61, v17
	v_cmp_lt_i32_e32 vcc, v13, v12
	s_waitcnt lgkmcnt(8)
	v_pk_add_f32 v[28:29], v[28:29], v[36:37]
	s_waitcnt lgkmcnt(6)
	v_pk_add_f32 v[36:37], v[86:87], v[40:41]
	v_cndmask_b32_e32 v12, v136, v13, vcc
	s_waitcnt lgkmcnt(4)
	v_pk_add_f32 v[44:45], v[18:19], v[44:45]
	s_waitcnt lgkmcnt(2)
	v_pk_add_f32 v[18:19], v[66:67], v[84:85]
	ds_bpermute_b32 v84, v54, v22
	ds_bpermute_b32 v85, v54, v23
	ds_bpermute_b32 v86, v54, v82
	ds_bpermute_b32 v87, v54, v83
	v_lshlrev_b32_e32 v63, 2, v12
	ds_bpermute_b32 v12, v54, v90
	ds_bpermute_b32 v13, v54, v91
	s_waitcnt lgkmcnt(6)
	v_pk_add_f32 v[16:17], v[16:17], v[24:25]
	ds_bpermute_b32 v24, v54, v88
	ds_bpermute_b32 v25, v54, v89
	s_waitcnt lgkmcnt(6)
; __device__ __forceinline__ void phase0(const Params& p, int wid_s, char* shm) {
;     ...
; #pragma unroll
;       for (int b = 0; b < 12; ++b)
; #pragma unroll
;         for (int c = 0; c < 4; ++c) {
;           float v = acc[b][c];
;           v += __shfl_xor(v, 8); v += __shfl_xor(v, 16); v += __shfl_xor(v, 32);
;           acc[b][c] = v;
;         }
	v_pk_add_f32 v[22:23], v[22:23], v[84:85]
	s_waitcnt lgkmcnt(4)
	v_pk_add_f32 v[86:87], v[82:83], v[86:87]
	ds_bpermute_b32 v2, v54, v92
	ds_bpermute_b32 v3, v54, v93
	s_waitcnt lgkmcnt(4)
	v_pk_add_f32 v[12:13], v[90:91], v[12:13]
	s_waitcnt lgkmcnt(2)
	v_pk_add_f32 v[24:25], v[88:89], v[24:25]
	ds_bpermute_b32 v84, v61, v22
	ds_bpermute_b32 v85, v61, v23
	ds_bpermute_b32 v88, v61, v86
	ds_bpermute_b32 v89, v61, v87
	ds_bpermute_b32 v90, v54, v26
	ds_bpermute_b32 v91, v54, v27
	s_waitcnt lgkmcnt(6)
	v_pk_add_f32 v[2:3], v[92:93], v[2:3]
	s_waitcnt lgkmcnt(4)
	v_pk_add_f32 v[82:83], v[22:23], v[84:85]
	s_waitcnt lgkmcnt(2)
	v_pk_add_f32 v[22:23], v[86:87], v[88:89]
	ds_bpermute_b32 v92, v54, v30
	s_waitcnt lgkmcnt(1)
	v_pk_add_f32 v[86:87], v[26:27], v[90:91]
	ds_bpermute_b32 v90, v54, v80
	ds_bpermute_b32 v91, v54, v81
	ds_bpermute_b32 v93, v54, v31
	ds_bpermute_b32 v96, v54, v34
	ds_bpermute_b32 v97, v54, v35
	ds_bpermute_b32 v100, v54, v76
	s_waitcnt lgkmcnt(4)
	v_pk_add_f32 v[80:81], v[80:81], v[90:91]
	s_waitcnt lgkmcnt(3)
	v_pk_add_f32 v[92:93], v[30:31], v[92:93]
	ds_bpermute_b32 v90, v61, v80
	ds_bpermute_b32 v91, v61, v81
	ds_bpermute_b32 v94, v61, v92
	ds_bpermute_b32 v95, v61, v93
	s_waitcnt lgkmcnt(5)
	v_pk_add_f32 v[96:97], v[34:35], v[96:97]
	ds_bpermute_b32 v98, v61, v96
	s_waitcnt lgkmcnt(3)
	v_pk_add_f32 v[30:31], v[80:81], v[90:91]
	ds_bpermute_b32 v99, v61, v97
	s_waitcnt lgkmcnt(2)
	v_pk_add_f32 v[90:91], v[92:93], v[94:95]
	ds_bpermute_b32 v94, v54, v78
	ds_bpermute_b32 v95, v54, v79
	ds_bpermute_b32 v101, v54, v77
	ds_bpermute_b32 v102, v54, v74
	ds_bpermute_b32 v103, v54, v75
	ds_bpermute_b32 v106, v54, v72
	s_waitcnt lgkmcnt(4)
	v_pk_add_f32 v[78:79], v[78:79], v[94:95]
	ds_bpermute_b32 v94, v61, v78
	ds_bpermute_b32 v95, v61, v79
	s_waitcnt lgkmcnt(3)
	v_pk_add_f32 v[102:103], v[74:75], v[102:103]
	ds_bpermute_b32 v104, v61, v102
	ds_bpermute_b32 v105, v61, v103
	ds_bpermute_b32 v107, v54, v73
	s_waitcnt lgkmcnt(3)
	v_pk_add_f32 v[34:35], v[78:79], v[94:95]
	v_pk_add_f32 v[94:95], v[96:97], v[98:99]
	v_pk_add_f32 v[96:97], v[76:77], v[100:101]
	ds_bpermute_b32 v100, v54, v38
	ds_bpermute_b32 v101, v54, v39
	s_waitcnt lgkmcnt(2)
	v_pk_add_f32 v[106:107], v[72:73], v[106:107]
	ds_bpermute_b32 v108, v61, v106
	ds_bpermute_b32 v109, v61, v107
	ds_bpermute_b32 v110, v54, v46
	s_waitcnt lgkmcnt(3)
	v_pk_add_f32 v[38:39], v[38:39], v[100:101]
	ds_bpermute_b32 v100, v61, v38
	ds_bpermute_b32 v101, v61, v39
	ds_bpermute_b32 v111, v54, v47
	ds_bpermute_b32 v8, v54, v6
	ds_bpermute_b32 v9, v54, v7
	ds_bpermute_b32 v112, v54, v68
	s_waitcnt lgkmcnt(4)
	v_pk_add_f32 v[74:75], v[38:39], v[100:101]
	v_pk_add_f32 v[38:39], v[102:103], v[104:105]
	ds_bpermute_b32 v104, v54, v42
	ds_bpermute_b32 v105, v54, v43
	ds_bpermute_b32 v113, v54, v69
	s_waitcnt lgkmcnt(4)
	v_pk_add_f32 v[6:7], v[6:7], v[8:9]
	ds_bpermute_b32 v4, v61, v2
	ds_bpermute_b32 v5, v61, v3
	s_waitcnt lgkmcnt(3)
	v_pk_add_f32 v[42:43], v[42:43], v[104:105]
	ds_bpermute_b32 v104, v61, v42
	ds_bpermute_b32 v105, v61, v43
	s_waitcnt lgkmcnt(4)
	v_pk_add_f32 v[112:113], v[68:69], v[112:113]
	ds_bpermute_b32 v8, v61, v6
	ds_bpermute_b32 v9, v61, v7
	ds_bpermute_b32 v20, v61, v12
	s_waitcnt lgkmcnt(3)
	v_pk_add_f32 v[72:73], v[42:43], v[104:105]
	v_pk_add_f32 v[42:43], v[106:107], v[108:109]
	v_pk_add_f32 v[106:107], v[46:47], v[110:111]
	ds_bpermute_b32 v110, v54, v70
	ds_bpermute_b32 v111, v54, v71
	ds_bpermute_b32 v21, v61, v13
	ds_bpermute_b32 v32, v61, v24
	ds_bpermute_b32 v33, v61, v25
	ds_bpermute_b32 v40, v61, v36
	s_waitcnt lgkmcnt(4)
	v_pk_add_f32 v[70:71], v[70:71], v[110:111]
	ds_bpermute_b32 v41, v61, v37
	ds_bpermute_b32 v88, v61, v86
	ds_bpermute_b32 v89, v61, v87
	ds_bpermute_b32 v98, v61, v96
	ds_bpermute_b32 v99, v61, v97
	ds_bpermute_b32 v108, v61, v106
	ds_bpermute_b32 v109, v61, v107
	ds_bpermute_b32 v110, v61, v70
	ds_bpermute_b32 v111, v61, v71
	ds_bpermute_b32 v138, v61, v112
	ds_bpermute_b32 v139, v61, v113
	v_pk_add_f32 v[2:3], v[2:3], v[4:5]
	v_pk_add_f32 v[6:7], v[6:7], v[8:9]
	s_waitcnt lgkmcnt(14)
	v_pk_add_f32 v[10:11], v[12:13], v[20:21]
	s_waitcnt lgkmcnt(12)
	v_pk_add_f32 v[14:15], v[24:25], v[32:33]
	s_waitcnt lgkmcnt(10)
	v_pk_add_f32 v[36:37], v[36:37], v[40:41]
	s_waitcnt lgkmcnt(8)
	v_pk_add_f32 v[86:87], v[86:87], v[88:89]
	s_waitcnt lgkmcnt(6)
	v_pk_add_f32 v[96:97], v[96:97], v[98:99]
	s_waitcnt lgkmcnt(4)
	v_pk_add_f32 v[106:107], v[106:107], v[108:109]
	s_waitcnt lgkmcnt(2)
	v_pk_add_f32 v[68:69], v[70:71], v[110:111]
	s_waitcnt lgkmcnt(0)
	v_pk_add_f32 v[110:111], v[112:113], v[138:139]
	ds_bpermute_b32 v4, v63, v2
	ds_bpermute_b32 v5, v63, v3
	ds_bpermute_b32 v8, v63, v6
	ds_bpermute_b32 v9, v63, v7
	ds_bpermute_b32 v12, v63, v10
	ds_bpermute_b32 v13, v63, v11
	ds_bpermute_b32 v20, v63, v16
	ds_bpermute_b32 v21, v63, v17
	ds_bpermute_b32 v24, v63, v14
	ds_bpermute_b32 v25, v63, v15
	ds_bpermute_b32 v32, v63, v28
	ds_bpermute_b32 v33, v63, v29
	ds_bpermute_b32 v40, v63, v36
	ds_bpermute_b32 v41, v63, v37
	ds_bpermute_b32 v48, v63, v44
	ds_bpermute_b32 v49, v63, v45
	ds_bpermute_b32 v66, v63, v18
	ds_bpermute_b32 v67, v63, v19
	ds_bpermute_b32 v84, v63, v82
	ds_bpermute_b32 v85, v63, v83
	ds_bpermute_b32 v26, v63, v22
	ds_bpermute_b32 v27, v63, v23
	ds_bpermute_b32 v88, v63, v86
	ds_bpermute_b32 v89, v63, v87
	ds_bpermute_b32 v80, v63, v30
	ds_bpermute_b32 v81, v63, v31
	ds_bpermute_b32 v92, v63, v90
	ds_bpermute_b32 v93, v63, v91
	ds_bpermute_b32 v78, v63, v34
	ds_bpermute_b32 v79, v63, v35
	ds_bpermute_b32 v76, v63, v94
	ds_bpermute_b32 v77, v63, v95
	ds_bpermute_b32 v98, v63, v96
	ds_bpermute_b32 v99, v63, v97
	ds_bpermute_b32 v100, v63, v74
	ds_bpermute_b32 v101, v63, v75
	ds_bpermute_b32 v102, v63, v38
	ds_bpermute_b32 v103, v63, v39
	ds_bpermute_b32 v104, v63, v72
	ds_bpermute_b32 v105, v63, v73
	ds_bpermute_b32 v46, v63, v42
	ds_bpermute_b32 v47, v63, v43
	ds_bpermute_b32 v108, v63, v106
	ds_bpermute_b32 v109, v63, v107
	ds_bpermute_b32 v70, v63, v68
	ds_bpermute_b32 v71, v63, v69
	ds_bpermute_b32 v112, v63, v110
	ds_bpermute_b32 v113, v63, v111
	s_and_saveexec_b64 s[6:7], s[12:13]
	s_cbranch_execz .LBB0_126
; __device__ __forceinline__ void phase0(const Params& p, int wid_s, char* shm) {
;     ...
;           v += __shfl_xor(v, 8); v += __shfl_xor(v, 16); v += __shfl_xor(v, 32);
;           acc[b][c] = v;
;         }
;       if (lane < 8) {
; #pragma unroll
;         for (int b = 0; b < 12; ++b)
; #pragma unroll
;           for (int c = 0; c < 4; ++c) red[(wid * 8 + lane) * 48 + b * 4 + c] = acc[b][c];
;       }
	s_waitcnt lgkmcnt(14)
	v_pk_add_f32 v[2:3], v[2:3], v[4:5]
	v_pk_add_f32 v[4:5], v[6:7], v[8:9]
	ds_write_b128 v134, v[2:5]
	v_pk_add_f32 v[2:3], v[10:11], v[12:13]
	v_pk_add_f32 v[4:5], v[16:17], v[20:21]
	ds_write_b128 v134, v[2:5] offset:16
	v_pk_add_f32 v[2:3], v[14:15], v[24:25]
	v_pk_add_f32 v[4:5], v[28:29], v[32:33]
	ds_write_b128 v134, v[2:5] offset:32
	v_pk_add_f32 v[2:3], v[36:37], v[40:41]
	v_pk_add_f32 v[4:5], v[44:45], v[48:49]
	ds_write_b128 v134, v[2:5] offset:48
	v_pk_add_f32 v[2:3], v[18:19], v[66:67]
	v_pk_add_f32 v[4:5], v[82:83], v[84:85]
	ds_write_b128 v134, v[2:5] offset:64
	v_pk_add_f32 v[2:3], v[22:23], v[26:27]
	v_pk_add_f32 v[4:5], v[86:87], v[88:89]
	ds_write_b128 v134, v[2:5] offset:80
	v_pk_add_f32 v[2:3], v[30:31], v[80:81]
	v_pk_add_f32 v[4:5], v[90:91], v[92:93]
	ds_write_b128 v134, v[2:5] offset:96
	v_pk_add_f32 v[2:3], v[34:35], v[78:79]
	v_pk_add_f32 v[4:5], v[94:95], v[76:77]
	ds_write_b128 v134, v[2:5] offset:112
	v_pk_add_f32 v[2:3], v[96:97], v[98:99]
	s_waitcnt lgkmcnt(14)
	v_pk_add_f32 v[4:5], v[74:75], v[100:101]
	ds_write_b128 v134, v[2:5] offset:128
	v_pk_add_f32 v[2:3], v[38:39], v[102:103]
	v_pk_add_f32 v[4:5], v[72:73], v[104:105]
	ds_write_b128 v134, v[2:5] offset:144
	v_pk_add_f32 v[2:3], v[42:43], v[46:47]
	s_waitcnt lgkmcnt(14)
	v_pk_add_f32 v[4:5], v[106:107], v[108:109]
	ds_write_b128 v134, v[2:5] offset:160
	s_waitcnt lgkmcnt(13)
	v_pk_add_f32 v[2:3], v[68:69], v[70:71]
	s_waitcnt lgkmcnt(11)
	v_pk_add_f32 v[4:5], v[110:111], v[112:113]
	ds_write_b128 v134, v[2:5] offset:176
